# attn inst1 (qb>=32 units): the 8 s_nop 2 per tile in the PV/exp block removed by retargeting the hazard exps to free VGPR pairs
# speedup vs baseline: 1.0295x; 1.0030x over previous
.LBB0_863:
	ds_read_b64_tr_b16 v[148:149], v215 offset:17408
	ds_read_b64_tr_b16 v[152:153], v215 offset:17440
	ds_read_b64_tr_b16 v[156:157], v215 offset:17472
	ds_read_b64_tr_b16 v[160:161], v215 offset:17504
	ds_read_b64_tr_b16 v[150:151], v215 offset:22016
	ds_read_b64_tr_b16 v[154:155], v215 offset:22048
	ds_read_b64_tr_b16 v[158:159], v215 offset:22080
	ds_read_b64_tr_b16 v[162:163], v215 offset:22112
	v_exp_f32_e32 v2, v144
	s_waitcnt lgkmcnt(3)
	v_mfma_f32_16x16x32_bf16 v[164:167], v[36:39], v[148:151], v[128:131]
	v_exp_f32_e32 v222, v145
	v_mfma_f32_16x16x32_bf16 v[148:151], v[60:63], v[148:151], v[120:123]
	v_exp_f32_e32 v224, v146
	s_waitcnt lgkmcnt(2)
	v_mfma_f32_16x16x32_bf16 v[124:127], v[36:39], v[152:155], v[124:127]
	v_exp_f32_e32 v122, v147
	v_mfma_f32_16x16x32_bf16 v[152:155], v[60:63], v[152:155], v[108:111]
	v_exp_f32_e32 v226, v44
	s_waitcnt lgkmcnt(1)
	v_mfma_f32_16x16x32_bf16 v[116:119], v[36:39], v[156:159], v[116:119]
	v_exp_f32_e32 v110, v45
	v_mfma_f32_16x16x32_bf16 v[168:171], v[60:63], v[156:159], v[100:103]
	v_exp_f32_e32 v228, v46
	s_waitcnt lgkmcnt(0)
	v_mfma_f32_16x16x32_bf16 v[104:107], v[36:39], v[160:163], v[104:107]
	v_exp_f32_e32 v100, v47
	v_mfma_f32_16x16x32_bf16 v[160:163], v[60:63], v[160:163], v[96:99]
	ds_read_b64_tr_b16 v[144:145], v215 offset:17536
	ds_read_b64_tr_b16 v[156:157], v215 offset:17568
	ds_read_b64_tr_b16 v[172:173], v215 offset:17600
	ds_read_b64_tr_b16 v[176:177], v215 offset:17632
	ds_read_b64_tr_b16 v[146:147], v215 offset:22144
	ds_read_b64_tr_b16 v[158:159], v215 offset:22176
	ds_read_b64_tr_b16 v[174:175], v215 offset:22208
	ds_read_b64_tr_b16 v[178:179], v215 offset:22240
	v_cvt_pk_bf16_f32 v44, v2, v222
	v_cvt_pk_bf16_f32 v45, v224, v122
	v_cvt_pk_bf16_f32 v46, v226, v110
	v_cvt_pk_bf16_f32 v47, v228, v100
	v_exp_f32_e32 v96, v140
	s_waitcnt lgkmcnt(3)
	v_mfma_f32_16x16x32_bf16 v[180:183], v[36:39], v[144:147], v[88:91]
	v_exp_f32_e32 v230, v141
	v_mfma_f32_16x16x32_bf16 v[184:187], v[60:63], v[144:147], v[76:79]
	v_exp_f32_e32 v232, v142
	s_waitcnt lgkmcnt(2)
	v_mfma_f32_16x16x32_bf16 v[80:83], v[36:39], v[156:159], v[80:83]
	v_exp_f32_e32 v78, v143
	v_mfma_f32_16x16x32_bf16 v[188:191], v[60:63], v[156:159], v[64:67]
	v_exp_f32_e32 v234, v72
	s_waitcnt lgkmcnt(1)
	v_mfma_f32_16x16x32_bf16 v[68:71], v[36:39], v[172:175], v[68:71]
	v_exp_f32_e32 v66, v73
	v_mfma_f32_16x16x32_bf16 v[192:195], v[60:63], v[172:175], v[52:55]
	v_exp_f32_e32 v236, v74
	s_waitcnt lgkmcnt(0)
	v_mfma_f32_16x16x32_bf16 v[56:59], v[36:39], v[176:179], v[56:59]
	v_exp_f32_e32 v54, v75
	v_mfma_f32_16x16x32_bf16 v[48:51], v[60:63], v[176:179], v[48:51]
	ds_read_b64_tr_b16 v[140:141], v215 offset:26624
	ds_read_b64_tr_b16 v[156:157], v215 offset:26656
	ds_read_b64_tr_b16 v[172:173], v215 offset:26688
	ds_read_b64_tr_b16 v[176:177], v215 offset:26720
	ds_read_b64_tr_b16 v[142:143], v215 offset:31232
	ds_read_b64_tr_b16 v[158:159], v215 offset:31264
	ds_read_b64_tr_b16 v[174:175], v215 offset:31296
	ds_read_b64_tr_b16 v[178:179], v215 offset:31328
	v_cvt_pk_bf16_f32 v72, v96, v230
	v_cvt_pk_bf16_f32 v73, v232, v78
	v_cvt_pk_bf16_f32 v74, v234, v66
	v_cvt_pk_bf16_f32 v75, v236, v54
	v_exp_f32_e32 v3, v136
	s_waitcnt lgkmcnt(3)
	v_mfma_f32_16x16x32_bf16 v[144:147], v[40:43], v[140:143], v[164:167]
	v_exp_f32_e32 v223, v137
	v_mfma_f32_16x16x32_bf16 v[140:143], v[84:87], v[140:143], v[148:151]
	v_exp_f32_e32 v225, v138
	s_waitcnt lgkmcnt(2)
	v_mfma_f32_16x16x32_bf16 v[148:151], v[40:43], v[156:159], v[124:127]
	v_exp_f32_e32 v123, v139
	v_mfma_f32_16x16x32_bf16 v[136:139], v[84:87], v[156:159], v[152:155]
	v_exp_f32_e32 v227, v92
	s_waitcnt lgkmcnt(1)
	v_mfma_f32_16x16x32_bf16 v[156:159], v[40:43], v[172:175], v[116:119]
	v_exp_f32_e32 v111, v93
	v_mfma_f32_16x16x32_bf16 v[152:155], v[84:87], v[172:175], v[168:171]
	v_exp_f32_e32 v229, v94
	s_waitcnt lgkmcnt(0)
	v_mfma_f32_16x16x32_bf16 v[164:167], v[40:43], v[176:179], v[104:107]
	v_exp_f32_e32 v101, v95
	v_mfma_f32_16x16x32_bf16 v[160:163], v[84:87], v[176:179], v[160:163]
	s_nop 0
	ds_read_b64_tr_b16 v[104:105], v215 offset:26752
	ds_read_b64_tr_b16 v[116:117], v215 offset:26784
	ds_read_b64_tr_b16 v[124:125], v215 offset:26816
	ds_read_b64_tr_b16 v[218:219], v215 offset:26848
	ds_read_b64_tr_b16 v[106:107], v215 offset:31360
	ds_read_b64_tr_b16 v[118:119], v215 offset:31392
	ds_read_b64_tr_b16 v[126:127], v215 offset:31424
	ds_read_b64_tr_b16 v[220:221], v215 offset:31456
	v_cvt_pk_bf16_f32 v92, v3, v223
	v_cvt_pk_bf16_f32 v93, v225, v123
	v_cvt_pk_bf16_f32 v94, v227, v111
	v_cvt_pk_bf16_f32 v95, v229, v101
	v_exp_f32_e32 v97, v132
	s_waitcnt lgkmcnt(3)
	v_mfma_f32_16x16x32_bf16 v[172:175], v[40:43], v[104:107], v[180:183]
	v_exp_f32_e32 v231, v133
	v_mfma_f32_16x16x32_bf16 v[168:171], v[84:87], v[104:107], v[184:187]
	v_exp_f32_e32 v233, v134
	s_waitcnt lgkmcnt(2)
	v_mfma_f32_16x16x32_bf16 v[176:179], v[40:43], v[116:119], v[80:83]
	v_exp_f32_e32 v79, v135
	v_mfma_f32_16x16x32_bf16 v[132:135], v[84:87], v[116:119], v[188:191]
	v_exp_f32_e32 v235, v112
	s_waitcnt lgkmcnt(1)
	v_mfma_f32_16x16x32_bf16 v[184:187], v[40:43], v[124:127], v[68:71]
	v_exp_f32_e32 v67, v113
	v_mfma_f32_16x16x32_bf16 v[180:183], v[84:87], v[124:127], v[192:195]
	v_exp_f32_e32 v237, v114
	s_waitcnt lgkmcnt(0)
	v_mfma_f32_16x16x32_bf16 v[192:195], v[40:43], v[218:221], v[56:59]
	v_exp_f32_e32 v55, v115
	v_mfma_f32_16x16x32_bf16 v[188:191], v[84:87], v[218:221], v[48:51]
	v_cvt_pk_bf16_f32 v112, v97, v231
	v_cvt_pk_bf16_f32 v113, v233, v79
	v_cvt_pk_bf16_f32 v114, v235, v67
	v_cvt_pk_bf16_f32 v115, v237, v55
	s_andn2_b64 vcc, exec, s[0:1]
	s_cbranch_vccnz .LBB0_865
	v_mov_b32_e32 v0, v210
	s_nop 0
	v_lshlrev_b32_e32 v0, 2, v0
	v_and_b32_e32 v0, 60, v0
	v_and_or_b32 v0, v212, 64, v0
	v_lshlrev_b32_e32 v0, 2, v0
	ds_bpermute_b32 v48, v0, v200
	ds_bpermute_b32 v50, v0, v200 offset:8
	ds_bpermute_b32 v51, v0, v200 offset:12
	ds_bpermute_b32 v49, v0, v200 offset:4
	ds_bpermute_b32 v56, v0, v201
	ds_bpermute_b32 v58, v0, v201 offset:8
	ds_bpermute_b32 v59, v0, v201 offset:12
	ds_bpermute_b32 v57, v0, v201 offset:4
	s_waitcnt lgkmcnt(5)
	v_pk_mul_f32 v[146:147], v[146:147], v[50:51]
	s_waitcnt lgkmcnt(4)
	v_pk_mul_f32 v[144:145], v[144:145], v[48:49]
	v_pk_mul_f32 v[150:151], v[150:151], v[50:51]
	v_pk_mul_f32 v[148:149], v[148:149], v[48:49]
	v_pk_mul_f32 v[158:159], v[158:159], v[50:51]
	v_pk_mul_f32 v[156:157], v[156:157], v[48:49]
	v_pk_mul_f32 v[166:167], v[166:167], v[50:51]
	v_pk_mul_f32 v[164:165], v[164:165], v[48:49]
	v_pk_mul_f32 v[174:175], v[174:175], v[50:51]
	v_pk_mul_f32 v[172:173], v[172:173], v[48:49]
	v_pk_mul_f32 v[178:179], v[178:179], v[50:51]
	v_pk_mul_f32 v[176:177], v[176:177], v[48:49]
	v_pk_mul_f32 v[186:187], v[186:187], v[50:51]
	v_pk_mul_f32 v[184:185], v[184:185], v[48:49]
	v_pk_mul_f32 v[194:195], v[194:195], v[50:51]
	v_pk_mul_f32 v[192:193], v[192:193], v[48:49]
	s_waitcnt lgkmcnt(1)
	v_pk_mul_f32 v[142:143], v[142:143], v[58:59]
	s_waitcnt lgkmcnt(0)
	v_pk_mul_f32 v[140:141], v[140:141], v[56:57]
	v_pk_mul_f32 v[138:139], v[138:139], v[58:59]
	v_pk_mul_f32 v[136:137], v[136:137], v[56:57]
	v_pk_mul_f32 v[154:155], v[154:155], v[58:59]
	v_pk_mul_f32 v[152:153], v[152:153], v[56:57]
	v_pk_mul_f32 v[162:163], v[162:163], v[58:59]
	v_pk_mul_f32 v[160:161], v[160:161], v[56:57]
	v_pk_mul_f32 v[170:171], v[170:171], v[58:59]
	v_pk_mul_f32 v[168:169], v[168:169], v[56:57]
	v_pk_mul_f32 v[134:135], v[134:135], v[58:59]
	v_pk_mul_f32 v[132:133], v[132:133], v[56:57]
	v_pk_mul_f32 v[182:183], v[182:183], v[58:59]
	v_pk_mul_f32 v[180:181], v[180:181], v[56:57]
	v_pk_mul_f32 v[190:191], v[190:191], v[58:59]
	v_pk_mul_f32 v[188:189], v[188:189], v[56:57]
.LBB0_865:
	v_pk_add_f32 v[2:3], v[198:199], v[2:3]
	s_nop 0
	v_pk_add_f32 v[2:3], v[222:223], v[2:3]
	s_nop 0
	v_pk_add_f32 v[2:3], v[224:225], v[2:3]
	s_nop 0
	v_pk_add_f32 v[2:3], v[122:123], v[2:3]
	s_nop 0
	v_pk_add_f32 v[2:3], v[226:227], v[2:3]
	s_nop 0
	v_pk_add_f32 v[2:3], v[110:111], v[2:3]
	s_nop 0
	v_pk_add_f32 v[2:3], v[228:229], v[2:3]
	s_nop 0
	v_pk_add_f32 v[2:3], v[100:101], v[2:3]
	s_nop 0
	v_pk_add_f32 v[2:3], v[96:97], v[2:3]
	s_nop 0
	v_pk_add_f32 v[2:3], v[230:231], v[2:3]
	s_nop 0
	v_pk_add_f32 v[2:3], v[232:233], v[2:3]
	s_nop 0
	v_pk_add_f32 v[2:3], v[78:79], v[2:3]
	s_nop 0
	v_pk_add_f32 v[2:3], v[234:235], v[2:3]
	s_nop 0
	v_pk_add_f32 v[2:3], v[66:67], v[2:3]
	s_nop 0
	v_pk_add_f32 v[2:3], v[236:237], v[2:3]
	s_nop 0
	v_pk_add_f32 v[198:199], v[54:55], v[2:3]

.LBB0_879:
	ds_read_b64_tr_b16 v[124:125], v215 offset:53248
	ds_read_b64_tr_b16 v[100:101], v215 offset:53280
	ds_read_b64_tr_b16 v[116:117], v215 offset:53312
	ds_read_b64_tr_b16 v[96:97], v215 offset:53344
	ds_read_b64_tr_b16 v[126:127], v215 offset:57856
	ds_read_b64_tr_b16 v[102:103], v215 offset:57888
	ds_read_b64_tr_b16 v[118:119], v215 offset:57920
	ds_read_b64_tr_b16 v[98:99], v215 offset:57952
	v_exp_f32_e32 v2, v128
	s_waitcnt lgkmcnt(3)
	v_mfma_f32_16x16x32_bf16 v[104:107], v[44:47], v[124:127], v[144:147]
	v_exp_f32_e32 v222, v129
	v_mfma_f32_16x16x32_bf16 v[124:127], v[92:95], v[124:127], v[140:143]
	v_exp_f32_e32 v224, v130
	s_waitcnt lgkmcnt(2)
	v_mfma_f32_16x16x32_bf16 v[148:151], v[44:47], v[100:103], v[148:151]
	v_exp_f32_e32 v142, v131
	v_mfma_f32_16x16x32_bf16 v[100:103], v[92:95], v[100:103], v[136:139]
	v_exp_f32_e32 v226, v36
	s_waitcnt lgkmcnt(1)
	v_mfma_f32_16x16x32_bf16 v[156:159], v[44:47], v[116:119], v[156:159]
	v_exp_f32_e32 v138, v37
	v_mfma_f32_16x16x32_bf16 v[76:79], v[92:95], v[116:119], v[152:155]
	v_exp_f32_e32 v228, v38
	s_waitcnt lgkmcnt(0)
	v_mfma_f32_16x16x32_bf16 v[164:167], v[44:47], v[96:99], v[164:167]
	v_exp_f32_e32 v154, v39
	v_mfma_f32_16x16x32_bf16 v[96:99], v[92:95], v[96:99], v[160:163]
	ds_read_b64_tr_b16 v[128:129], v215 offset:53376
	ds_read_b64_tr_b16 v[116:117], v215 offset:53408
	ds_read_b64_tr_b16 v[88:89], v215 offset:53440
	ds_read_b64_tr_b16 v[80:81], v215 offset:53472
	ds_read_b64_tr_b16 v[130:131], v215 offset:57984
	ds_read_b64_tr_b16 v[118:119], v215 offset:58016
	ds_read_b64_tr_b16 v[90:91], v215 offset:58048
	ds_read_b64_tr_b16 v[82:83], v215 offset:58080
	v_cvt_pk_bf16_f32 v36, v2, v222
	v_cvt_pk_bf16_f32 v37, v224, v142
	v_cvt_pk_bf16_f32 v38, v226, v138
	v_cvt_pk_bf16_f32 v39, v228, v154
	v_exp_f32_e32 v160, v120
	s_waitcnt lgkmcnt(3)
	v_mfma_f32_16x16x32_bf16 v[52:55], v[44:47], v[128:131], v[172:175]
	v_exp_f32_e32 v230, v121
	v_mfma_f32_16x16x32_bf16 v[68:71], v[92:95], v[128:131], v[168:171]
	v_exp_f32_e32 v232, v122
	s_waitcnt lgkmcnt(2)
	v_mfma_f32_16x16x32_bf16 v[176:179], v[44:47], v[116:119], v[176:179]
	v_exp_f32_e32 v170, v123
	v_mfma_f32_16x16x32_bf16 v[48:51], v[92:95], v[116:119], v[132:135]
	v_exp_f32_e32 v234, v40
	s_waitcnt lgkmcnt(1)
	v_mfma_f32_16x16x32_bf16 v[184:187], v[44:47], v[88:91], v[184:187]
	v_exp_f32_e32 v134, v41
	v_mfma_f32_16x16x32_bf16 v[56:59], v[92:95], v[88:91], v[180:183]
	v_exp_f32_e32 v236, v42
	s_waitcnt lgkmcnt(0)
	v_mfma_f32_16x16x32_bf16 v[192:195], v[44:47], v[80:83], v[192:195]
	v_exp_f32_e32 v182, v43
	v_mfma_f32_16x16x32_bf16 v[188:191], v[92:95], v[80:83], v[188:191]
	ds_read_b64_tr_b16 v[120:121], v215 offset:62464
	ds_read_b64_tr_b16 v[116:117], v215 offset:62496
	ds_read_b64_tr_b16 v[88:89], v215 offset:62528
	ds_read_b64_tr_b16 v[80:81], v215 offset:62560
	ds_read_b64_tr_b16 v[122:123], v216 offset:13824
	ds_read_b64_tr_b16 v[118:119], v216 offset:13856
	ds_read_b64_tr_b16 v[90:91], v216 offset:13888
	ds_read_b64_tr_b16 v[82:83], v216 offset:13920
	v_cvt_pk_bf16_f32 v40, v160, v230
	v_cvt_pk_bf16_f32 v41, v232, v170
	v_cvt_pk_bf16_f32 v42, v234, v134
	v_cvt_pk_bf16_f32 v43, v236, v182
	v_exp_f32_e32 v3, v108
	s_waitcnt lgkmcnt(3)
	v_mfma_f32_16x16x32_bf16 v[128:131], v[72:75], v[120:123], v[104:107]
	v_exp_f32_e32 v223, v109
	v_mfma_f32_16x16x32_bf16 v[120:123], v[112:115], v[120:123], v[124:127]
	v_exp_f32_e32 v225, v110
	s_waitcnt lgkmcnt(2)
	v_mfma_f32_16x16x32_bf16 v[124:127], v[72:75], v[116:119], v[148:151]
	v_exp_f32_e32 v143, v111
	v_mfma_f32_16x16x32_bf16 v[108:111], v[112:115], v[116:119], v[100:103]
	v_exp_f32_e32 v227, v60
	s_waitcnt lgkmcnt(1)
	v_mfma_f32_16x16x32_bf16 v[116:119], v[72:75], v[88:91], v[156:159]
	v_exp_f32_e32 v139, v61
	v_mfma_f32_16x16x32_bf16 v[100:103], v[112:115], v[88:91], v[76:79]
	v_exp_f32_e32 v229, v62
	s_waitcnt lgkmcnt(0)
	v_mfma_f32_16x16x32_bf16 v[104:107], v[72:75], v[80:83], v[164:167]
	v_exp_f32_e32 v155, v63
	v_mfma_f32_16x16x32_bf16 v[96:99], v[112:115], v[80:83], v[96:99]
	s_nop 0
	ds_read_b64_tr_b16 v[164:165], v215 offset:62592
	ds_read_b64_tr_b16 v[156:157], v215 offset:62624
	ds_read_b64_tr_b16 v[148:149], v215 offset:62656
	ds_read_b64_tr_b16 v[218:219], v215 offset:62688
	ds_read_b64_tr_b16 v[166:167], v216 offset:13952
	ds_read_b64_tr_b16 v[158:159], v216 offset:13984
	ds_read_b64_tr_b16 v[150:151], v216 offset:14016
	ds_read_b64_tr_b16 v[220:221], v216 offset:14048
	v_cvt_pk_bf16_f32 v60, v3, v223
	v_cvt_pk_bf16_f32 v61, v225, v143
	v_cvt_pk_bf16_f32 v62, v227, v139
	v_cvt_pk_bf16_f32 v63, v229, v155
	v_exp_f32_e32 v161, v64
	s_waitcnt lgkmcnt(3)
	v_mfma_f32_16x16x32_bf16 v[88:91], v[72:75], v[164:167], v[52:55]
	v_exp_f32_e32 v231, v65
	v_mfma_f32_16x16x32_bf16 v[76:79], v[112:115], v[164:167], v[68:71]
	v_exp_f32_e32 v233, v66
	s_waitcnt lgkmcnt(2)
	v_mfma_f32_16x16x32_bf16 v[80:83], v[72:75], v[156:159], v[176:179]
	v_exp_f32_e32 v171, v67
	v_mfma_f32_16x16x32_bf16 v[64:67], v[112:115], v[156:159], v[48:51]
	v_exp_f32_e32 v235, v84
	s_waitcnt lgkmcnt(1)
	v_mfma_f32_16x16x32_bf16 v[68:71], v[72:75], v[148:151], v[184:187]
	v_exp_f32_e32 v135, v85
	v_mfma_f32_16x16x32_bf16 v[52:55], v[112:115], v[148:151], v[56:59]
	v_exp_f32_e32 v237, v86
	s_waitcnt lgkmcnt(0)
	v_mfma_f32_16x16x32_bf16 v[56:59], v[72:75], v[218:221], v[192:195]
	v_exp_f32_e32 v183, v87
	v_mfma_f32_16x16x32_bf16 v[48:51], v[112:115], v[218:221], v[188:191]
	v_cvt_pk_bf16_f32 v84, v161, v231
	v_cvt_pk_bf16_f32 v85, v233, v171
	v_cvt_pk_bf16_f32 v86, v235, v135
	v_cvt_pk_bf16_f32 v87, v237, v183
	s_andn2_b64 vcc, exec, s[2:3]
	s_cbranch_vccnz .LBB0_881
	v_mov_b32_e32 v0, v210
	s_nop 0
	v_lshlrev_b32_e32 v0, 2, v0
	v_and_b32_e32 v0, 60, v0
	v_and_or_b32 v0, v212, 64, v0
	v_lshlrev_b32_e32 v0, 2, v0
	ds_bpermute_b32 v188, v0, v200
	ds_bpermute_b32 v190, v0, v200 offset:8
	ds_bpermute_b32 v191, v0, v200 offset:12
	ds_bpermute_b32 v189, v0, v200 offset:4
	ds_bpermute_b32 v192, v0, v201
	ds_bpermute_b32 v194, v0, v201 offset:8
	ds_bpermute_b32 v195, v0, v201 offset:12
	ds_bpermute_b32 v193, v0, v201 offset:4
	s_waitcnt lgkmcnt(5)
	v_pk_mul_f32 v[130:131], v[130:131], v[190:191]
	s_waitcnt lgkmcnt(4)
	v_pk_mul_f32 v[128:129], v[128:129], v[188:189]
	v_pk_mul_f32 v[126:127], v[126:127], v[190:191]
	v_pk_mul_f32 v[124:125], v[124:125], v[188:189]
	v_pk_mul_f32 v[118:119], v[118:119], v[190:191]
	v_pk_mul_f32 v[116:117], v[116:117], v[188:189]
	v_pk_mul_f32 v[106:107], v[106:107], v[190:191]
	v_pk_mul_f32 v[104:105], v[104:105], v[188:189]
	v_pk_mul_f32 v[90:91], v[90:91], v[190:191]
	v_pk_mul_f32 v[88:89], v[88:89], v[188:189]
	v_pk_mul_f32 v[82:83], v[82:83], v[190:191]
	v_pk_mul_f32 v[80:81], v[80:81], v[188:189]
	v_pk_mul_f32 v[70:71], v[70:71], v[190:191]
	v_pk_mul_f32 v[68:69], v[68:69], v[188:189]
	v_pk_mul_f32 v[58:59], v[58:59], v[190:191]
	v_pk_mul_f32 v[56:57], v[56:57], v[188:189]
	s_waitcnt lgkmcnt(1)
	v_pk_mul_f32 v[122:123], v[122:123], v[194:195]
	s_waitcnt lgkmcnt(0)
	v_pk_mul_f32 v[120:121], v[120:121], v[192:193]
	v_pk_mul_f32 v[110:111], v[110:111], v[194:195]
	v_pk_mul_f32 v[108:109], v[108:109], v[192:193]
	v_pk_mul_f32 v[102:103], v[102:103], v[194:195]
	v_pk_mul_f32 v[100:101], v[100:101], v[192:193]
	v_pk_mul_f32 v[98:99], v[98:99], v[194:195]
	v_pk_mul_f32 v[96:97], v[96:97], v[192:193]
	v_pk_mul_f32 v[78:79], v[78:79], v[194:195]
	v_pk_mul_f32 v[76:77], v[76:77], v[192:193]
	v_pk_mul_f32 v[66:67], v[66:67], v[194:195]
	v_pk_mul_f32 v[64:65], v[64:65], v[192:193]
	v_pk_mul_f32 v[54:55], v[54:55], v[194:195]
	v_pk_mul_f32 v[52:53], v[52:53], v[192:193]
	v_pk_mul_f32 v[50:51], v[50:51], v[194:195]
	v_pk_mul_f32 v[48:49], v[48:49], v[192:193]
.LBB0_881:
	v_pk_add_f32 v[2:3], v[198:199], v[2:3]
	s_nop 0
	v_pk_add_f32 v[2:3], v[222:223], v[2:3]
	s_nop 0
	v_pk_add_f32 v[2:3], v[224:225], v[2:3]
	s_nop 0
	v_pk_add_f32 v[2:3], v[142:143], v[2:3]
	s_nop 0
	v_pk_add_f32 v[2:3], v[226:227], v[2:3]
	s_nop 0
	v_pk_add_f32 v[2:3], v[138:139], v[2:3]
	s_nop 0
	v_pk_add_f32 v[2:3], v[228:229], v[2:3]
	s_nop 0
	v_pk_add_f32 v[2:3], v[154:155], v[2:3]
	s_nop 0
	v_pk_add_f32 v[2:3], v[160:161], v[2:3]
	s_nop 0
	v_pk_add_f32 v[2:3], v[230:231], v[2:3]
	s_nop 0
	v_pk_add_f32 v[2:3], v[232:233], v[2:3]
	s_nop 0
	v_pk_add_f32 v[2:3], v[170:171], v[2:3]
	s_nop 0
	v_pk_add_f32 v[2:3], v[234:235], v[2:3]
	s_nop 0
	v_pk_add_f32 v[2:3], v[134:135], v[2:3]
	s_nop 0
	v_pk_add_f32 v[2:3], v[236:237], v[2:3]
	s_nop 0
	v_pk_add_f32 v[198:199], v[182:183], v[2:3]
